# comb18 + phase stagger: in the layer-0 out-proj and down GEMMs the workgroups that own 4 tiles (instead of 5) start half a tile late so their residual-update epilogues do not collide with the others'
# speedup vs baseline: 1.0037x; 1.0036x over previous
;     __device__ __forceinline__ bool next(int i, Unit& u) const {
;         const long L = (long)i * G + c; if (L >= nwg) return false;
;         int w = (int)L; { const int q = nwg / NXCD, r = nwg % NXCD, xcd = w % NXCD, off = w / NXCD; w = (xcd < r ? xcd * (q + 1) : r * (q + 1) + (xcd - r) * q) + off; }
;         u.pb = w / per; w -= u.pb * per;
;         const int nig = WGM * nN, gid = w / nig, fm = gid * WGM, gsz = (nM - fm) < WGM ? (nM - fm) : WGM;
; template <class Epi>
; __device__ __forceinline__ void gemm_phase(LAS unsigned char* lds, const Gemm g, int G, int c, const Epi& E) {
;     ...
;     const int wid = __builtin_amdgcn_readfirstlane(tid >> 6), lane = tid & 63, wr = wid >> 2, wc = wid & 3, fr = lane & 15, fq = lane >> 4;
;     const int nt = g.K / BK;
;     Order S; S.init(g, G, c);
;     unsigned voffA[2], voffB[2];
; #pragma unroll
;     for (int i = 0; i < 2; ++i) { int R, C; stage_rc(tid * 16 + i * 8192, R, C); const int Rb = Epi::PERM ? ((R & ~31) + perm32(R & 31)) : R;
;         voffA[i] = (unsigned)(R * g.ld + C) * 2u; voffB[i] = Epi::PERM ? (unsigned)(Rb * g.ld + C) * 2u : voffA[i]; }
;     const size_t kstep = (size_t)(BK * 2);
;     const size_t hstepA = (size_t)HALF * g.ld * 2, hstepB = hstepA;
;     const unsigned ldsw = (unsigned)wid * 1024u;
;     const int aoff = lds_byte(wr * 64 + fr, fq * 8), boff = lds_byte(wc * 32 + fr, fq * 8);
;     ...
;     Unit cur, nxt; int ui = 0;
;     if (!S.next(0, cur)) return;
;     f32x4 acc[2][2][4][2];
; #pragma unroll
;     for (int a = 0; a < 2; ++a)
; #pragma unroll
;         for (int b = 0; b < 2; ++b)
; #pragma unroll
;             for (int m = 0; m < 4; ++m)
; #pragma unroll
;                 for (int n = 0; n < 2; ++n) acc[a][b][m][n] = (f32x4){0.f, 0.f, 0.f, 0.f};
;     bf16x8 At[4][2], B0[2][2], B1[2][2];
;     const char* cA = (const char*)(g.A + (size_t)cur.pb * g.sA) + (size_t)cur.pm * 2 * hstepA;
;     const char* cB = (const char*)(g.Bt + (size_t)cur.pb * g.sB) + (size_t)cur.pn * 2 * hstepB;
;     PG8_STAGE(PG8_SB(0, 0), cB, voffB); PG8_STAGE(PG8_SB(0, 1), cB + hstepB, voffB); PG8_STAGE(PG8_SA(0, 0), cA, voffA); PG8_STAGE(PG8_SA(0, 1), cA + hstepA, voffA);
;     if (wr == 1) PG8_BAR;
;     PG8_WAIT_V(2); PG8_BAR;
;     PG8_STAGE(PG8_SB(1, 0), cB + kstep, voffB); PG8_STAGE(PG8_SA(1, 0), cA + kstep, voffA); PG8_STAGE(PG8_SB(1, 1), cB + hstepB + kstep, voffB);
;     PG8_WAIT_V(6); PG8_BAR;
.LBB0_890:
.LBB0_891:
	s_cmp_gt_i32 s76, 5
	s_cselect_b64 s[2:3], -1, 0
	s_cmp_lt_i32 s77, 6
	s_cselect_b64 s[4:5], -1, 0
	s_or_b64 s[2:3], s[2:3], s[4:5]
	s_and_b64 vcc, exec, s[2:3]
	s_cbranch_vccnz .LBB0_978
	s_cmp_lt_u32 s26, 0x80
	s_cbranch_scc1 .Lstg_p5
	s_sleep 127
	s_sleep 127
	s_sleep 127
	s_sleep 127
	s_sleep 127
.Lstg_p5:
	s_load_dword s27, s[0:1], 0xb8
	s_add_u32 s6, s0, 0xb8
	v_and_b32_e32 v1, 0x3ff, v0
	s_addc_u32 s7, s1, 0
	v_mov_b32_e32 v2, v1
	v_mov_b32_e32 v11, v1
	s_cmpk_gt_i32 s26, 0x47f
	v_readfirstlane_b32 s2, v11
	s_cbranch_scc1 .LBB0_914
	v_lshlrev_b32_e32 v2, 4, v11
	s_waitcnt lgkmcnt(0)
	v_add_u32_e32 v3, 0x2000, v2
	v_ashrrev_i32_e32 v4, 31, v3
	v_lshrrev_b32_e32 v4, 22, v4
	v_add_u32_e32 v4, v3, v4
	v_ashrrev_i32_e32 v10, 10, v4
	v_mul_i32_i24_e32 v4, 0x400, v10
	v_sub_u32_e32 v3, v3, v4
	v_lshrrev_b32_e32 v4, 4, v3
	v_bitop3_b32 v3, v4, v3, 32 bitop3:0x6c
	v_ashrrev_i32_e32 v4, 31, v3
	v_lshrrev_b32_e32 v4, 26, v4
	v_add_u32_e32 v4, v3, v4
	v_lshlrev_b32_e32 v5, 3, v10
	v_ashrrev_i32_e32 v12, 6, v4
	v_and_b32_e32 v5, -16, v5
	v_add_u32_e32 v5, v12, v5
	v_and_b32_e32 v6, 3, v12
	s_mov_b32 s5, 0x1fffe0
	v_lshrrev_b32_e32 v7, 2, v5
	v_lshlrev_b32_e32 v8, 1, v5
	v_and_b32_e32 v4, 0xc0, v4
	v_and_or_b32 v6, v5, s5, v6
	v_and_b32_e32 v7, 4, v7
	v_and_b32_e32 v8, 24, v8
	v_sub_u32_e32 v3, v3, v4
	v_mov_b32_e32 v4, 1
	v_or3_b32 v6, v6, v7, v8
	v_lshlrev_b32_e32 v7, 5, v10
	v_ashrrev_i16_sdwa v3, v4, sext(v3) dst_sel:DWORD dst_unused:UNUSED_PAD src0_sel:DWORD src1_sel:BYTE_0
	v_and_b32_e32 v7, 32, v7
	v_bfe_i32 v13, v3, 0, 16
	v_add_lshl_u32 v3, v7, v13, 1
	v_lshl_add_u32 v146, v6, 11, v3
	v_lshl_add_u32 v148, v5, 11, v3
	v_bfe_i32 v3, v11, 27, 1
	v_lshrrev_b32_e32 v3, 22, v3
	v_add_u32_e32 v3, v2, v3
	v_and_b32_e32 v3, 0xfffffc00, v3
	v_sub_u32_e32 v2, v2, v3
	v_lshrrev_b32_e32 v3, 4, v2
	v_ashrrev_i32_e32 v5, 31, v11
	v_bitop3_b32 v2, v3, v2, 32 bitop3:0x6c
	v_lshrrev_b32_e32 v5, 26, v5
	v_ashrrev_i32_e32 v3, 31, v2
	v_add_u32_e32 v5, v11, v5
	s_add_u32 s34, s30, 0x2c00000
	v_lshrrev_b32_e32 v3, 26, v3
	v_ashrrev_i32_e32 v15, 6, v5
	s_addc_u32 s35, s31, 0
	v_add_u32_e32 v3, v2, v3
	v_lshlrev_b32_e32 v5, 3, v15
	s_add_u32 s52, s30, 0x1d92c000
	v_ashrrev_i32_e32 v14, 6, v3
	v_and_b32_e32 v5, -16, v5
	s_addc_u32 s53, s31, 0
	s_ashr_i32 s55, s26, 31
	v_add_u32_e32 v5, v14, v5
	v_and_b32_e32 v6, 3, v14
	v_and_or_b32 v6, v5, s5, v6
	s_lshr_b32 s5, s55, 29
	s_add_i32 s5, s26, s5
	s_ashr_i32 s3, s2, 6
	s_ashr_i32 s8, s5, 3
	s_and_b32 s5, s5, -8
	s_ashr_i32 s4, s2, 8
	s_lshl_b32 s54, s3, 10
	s_sub_i32 s5, s26, s5
	s_cmp_lt_i32 s5, 0
	s_movk_i32 s56, 0x91
	s_cselect_b32 s9, s56, 0x90
	s_mul_i32 s5, s9, s5
	s_add_i32 s5, s5, s8
	s_mul_hi_i32 s8, s5, 0x38e38e39
	s_lshr_b32 s9, s8, 31
	s_ashr_i32 s8, s8, 3
	s_add_i32 s22, s8, s9
	s_mul_i32 s8, s22, 0xffffffdc
	s_add_i32 s5, s8, s5
	s_ashr_i32 s8, s5, 31
	s_lshr_b32 s8, s8, 27
	s_add_i32 s8, s5, s8
	s_ashr_i32 s9, s8, 5
	s_lshl_b32 s9, s9, 3
	v_and_b32_e32 v3, 0xc0, v3
	s_sub_i32 s10, 9, s9
	v_sub_u32_e32 v2, v2, v3
	s_min_i32 s10, s10, 8
	v_ashrrev_i16_sdwa v2, v4, sext(v2) dst_sel:DWORD dst_unused:UNUSED_PAD src0_sel:DWORD src1_sel:BYTE_0
	s_abs_i32 s11, s10
	v_bfe_i32 v16, v2, 0, 16
	v_cvt_f32_u32_e32 v2, s11
	s_sub_i32 s13, 0, s11
	s_andn2_b32 s8, s8, 31
	s_sub_i32 s5, s5, s8
	v_rcp_iflag_f32_e32 v2, v2
	s_abs_i32 s12, s5
	s_xor_b32 s8, s5, s10
	s_ashr_i32 s8, s8, 31
	v_mul_f32_e32 v2, 0x4f7ffffe, v2
	v_cvt_u32_f32_e32 v2, v2
	v_lshrrev_b32_e32 v7, 2, v5
	v_lshlrev_b32_e32 v8, 1, v5
	v_and_b32_e32 v7, 4, v7
	v_readfirstlane_b32 s14, v2
	s_mul_i32 s13, s13, s14
	s_mul_hi_u32 s13, s14, s13
	s_add_i32 s14, s14, s13
	s_mul_hi_u32 s13, s12, s14
	s_mul_i32 s14, s13, s11
	s_sub_i32 s12, s12, s14
	s_add_i32 s14, s13, 1
	s_sub_i32 s15, s12, s11
	s_cmp_ge_u32 s12, s11
	s_cselect_b32 s13, s14, s13
	s_cselect_b32 s12, s15, s12
	s_add_i32 s14, s13, 1
	s_cmp_ge_u32 s12, s11
	s_cselect_b32 s11, s14, s13
	s_xor_b32 s11, s11, s8
	s_sub_i32 s24, s11, s8
	s_mul_i32 s8, s24, s10
	s_sub_i32 s5, s5, s8
	s_add_i32 s38, s5, s9
	v_and_b32_e32 v8, 24, v8
	s_ashr_i32 s39, s38, 31
	s_ashr_i32 s25, s24, 31
	v_or3_b32 v6, v6, v7, v8
	v_lshlrev_b32_e32 v7, 5, v15
	s_lshl_b64 s[8:9], s[38:39], 19
	s_lshl_b64 s[10:11], s[24:25], 19
	v_and_b32_e32 v7, 32, v7
	s_add_u32 s42, s34, s10
	v_add_lshl_u32 v3, v7, v16, 1
	s_addc_u32 s43, s35, s11
	s_add_i32 s25, s54, 0
	v_lshl_add_u32 v150, v6, 11, v3
	s_add_i32 m0, s25, 0x10000
	s_mul_i32 s12, s22, 0x480000
	global_load_lds_dwordx4 v150, s[42:43]
	s_add_i32 m0, s25, 0x12000
	s_mul_hi_i32 s5, s22, 0x480000
	s_add_u32 s12, s52, s12
	s_addc_u32 s5, s53, s5
	s_add_u32 s10, s42, 0x40000
	global_load_lds_dwordx4 v146, s[42:43]
	s_addc_u32 s11, s43, 0
	s_add_i32 m0, s25, 0x14000
	v_lshl_add_u32 v152, v5, 11, v3
	global_load_lds_dwordx4 v150, s[10:11]
	s_add_i32 m0, s25, 0x16000
	s_add_u32 s44, s12, s8
	s_addc_u32 s45, s5, s9
	s_add_i32 s57, s25, 0x2000
	global_load_lds_dwordx4 v146, s[10:11]
	s_mov_b32 m0, s25
	s_add_u32 s8, s44, 0x40000
	global_load_lds_dwordx4 v152, s[44:45]
	s_mov_b32 m0, s57
	s_addc_u32 s9, s45, 0
	s_add_i32 s58, s25, 0x4000
	global_load_lds_dwordx4 v148, s[44:45]
	s_mov_b32 m0, s58
	s_add_i32 s59, s25, 0x6000
	global_load_lds_dwordx4 v152, s[8:9]
	s_mov_b32 m0, s59
	v_mov_b32_e32 v151, 0
	global_load_lds_dwordx4 v148, s[8:9]
	v_mov_b32_e32 v147, v151
	v_mov_b32_e32 v153, v151
	v_mov_b32_e32 v149, v151
	s_cmp_eq_u32 s4, 1
	s_mov_b32 s60, 0
	v_lshl_add_u64 v[8:9], s[42:43], 0, v[150:151]
	v_lshl_add_u64 v[6:7], s[42:43], 0, v[146:147]
	v_lshl_add_u64 v[2:3], s[44:45], 0, v[152:153]
	s_cselect_b64 s[8:9], -1, 0
	s_cmp_lg_u32 s4, 1
	v_lshl_add_u64 v[4:5], s[44:45], 0, v[148:149]
	s_cbranch_scc1 .LBB0_895
	s_barrier

;     __device__ __forceinline__ bool next(int i, Unit& u) const {
;         const long L = (long)i * G + c; if (L >= nwg) return false;
;         int w = (int)L; { const int q = nwg / NXCD, r = nwg % NXCD, xcd = w % NXCD, off = w / NXCD; w = (xcd < r ? xcd * (q + 1) : r * (q + 1) + (xcd - r) * q) + off; }
;         u.pb = w / per; w -= u.pb * per;
;         const int nig = WGM * nN, gid = w / nig, fm = gid * WGM, gsz = (nM - fm) < WGM ? (nM - fm) : WGM;
; template <class Epi>
; __device__ __forceinline__ void gemm_phase(LAS unsigned char* lds, const Gemm g, int G, int c, const Epi& E) {
;     ...
;     const int wid = __builtin_amdgcn_readfirstlane(tid >> 6), lane = tid & 63, wr = wid >> 2, wc = wid & 3, fr = lane & 15, fq = lane >> 4;
;     const int nt = g.K / BK;
;     Order S; S.init(g, G, c);
;     unsigned voffA[2], voffB[2];
; #pragma unroll
;     for (int i = 0; i < 2; ++i) { int R, C; stage_rc(tid * 16 + i * 8192, R, C); const int Rb = Epi::PERM ? ((R & ~31) + perm32(R & 31)) : R;
;         voffA[i] = (unsigned)(R * g.ld + C) * 2u; voffB[i] = Epi::PERM ? (unsigned)(Rb * g.ld + C) * 2u : voffA[i]; }
;     const size_t kstep = (size_t)(BK * 2);
;     const size_t hstepA = (size_t)HALF * g.ld * 2, hstepB = hstepA;
;     const unsigned ldsw = (unsigned)wid * 1024u;
;     const int aoff = lds_byte(wr * 64 + fr, fq * 8), boff = lds_byte(wc * 32 + fr, fq * 8);
;     ...
;     Unit cur, nxt; int ui = 0;
;     if (!S.next(0, cur)) return;
;     f32x4 acc[2][2][4][2];
; #pragma unroll
;     for (int a = 0; a < 2; ++a)
; #pragma unroll
;         for (int b = 0; b < 2; ++b)
; #pragma unroll
;             for (int m = 0; m < 4; ++m)
; #pragma unroll
;                 for (int n = 0; n < 2; ++n) acc[a][b][m][n] = (f32x4){0.f, 0.f, 0.f, 0.f};
;     bf16x8 At[4][2], B0[2][2], B1[2][2];
;     const char* cA = (const char*)(g.A + (size_t)cur.pb * g.sA) + (size_t)cur.pm * 2 * hstepA;
;     const char* cB = (const char*)(g.Bt + (size_t)cur.pb * g.sB) + (size_t)cur.pn * 2 * hstepB;
;     PG8_STAGE(PG8_SB(0, 0), cB, voffB); PG8_STAGE(PG8_SB(0, 1), cB + hstepB, voffB); PG8_STAGE(PG8_SA(0, 0), cA, voffA); PG8_STAGE(PG8_SA(0, 1), cA + hstepA, voffA);
;     if (wr == 1) PG8_BAR;
;     PG8_WAIT_V(2); PG8_BAR;
;     PG8_STAGE(PG8_SB(1, 0), cB + kstep, voffB); PG8_STAGE(PG8_SA(1, 0), cA + kstep, voffA); PG8_STAGE(PG8_SB(1, 1), cB + hstepB + kstep, voffB);
;     PG8_WAIT_V(6); PG8_BAR;
.LBB0_1129:
	s_cmp_gt_i32 s76, 8
	s_cselect_b64 s[2:3], -1, 0
	s_cmp_lt_i32 s77, 9
	s_cselect_b64 s[4:5], -1, 0
	s_or_b64 s[2:3], s[2:3], s[4:5]
	s_and_b64 vcc, exec, s[2:3]
	s_cbranch_vccnz .LBB0_1214
	s_cmp_lt_u32 s26, 0x80
	s_cbranch_scc1 .Lstg_p8
	s_sleep 127
	s_sleep 127
	s_sleep 127
	s_sleep 127
	s_sleep 127
	s_sleep 127
	s_sleep 127
	s_sleep 127
	s_sleep 127
	s_sleep 127
.Lstg_p8:
	s_load_dword s24, s[0:1], 0xb8
	s_add_u32 s6, s0, 0xb8
	v_and_b32_e32 v1, 0x3ff, v0
	s_addc_u32 s7, s1, 0
	v_mov_b32_e32 v2, v1
	v_mov_b32_e32 v11, v1
	s_cmpk_gt_i32 s26, 0x47f
	v_readfirstlane_b32 s2, v11
	s_cbranch_scc1 .LBB0_1150
	v_lshlrev_b32_e32 v2, 4, v11
	s_waitcnt lgkmcnt(0)
	v_add_u32_e32 v3, 0x2000, v2
	v_ashrrev_i32_e32 v4, 31, v3
	v_lshrrev_b32_e32 v4, 22, v4
	v_add_u32_e32 v4, v3, v4
	v_ashrrev_i32_e32 v10, 10, v4
	v_mul_i32_i24_e32 v4, 0x400, v10
	v_sub_u32_e32 v3, v3, v4
	v_lshrrev_b32_e32 v4, 4, v3
	v_bitop3_b32 v3, v4, v3, 32 bitop3:0x6c
	v_ashrrev_i32_e32 v4, 31, v3
	v_lshrrev_b32_e32 v4, 26, v4
	v_add_u32_e32 v4, v3, v4
	v_lshlrev_b32_e32 v5, 3, v10
	v_ashrrev_i32_e32 v12, 6, v4
	v_and_b32_e32 v5, -16, v5
	v_add_u32_e32 v5, v12, v5
	v_and_b32_e32 v6, 3, v12
	s_mov_b32 s8, 0xffffe0
	v_lshrrev_b32_e32 v7, 2, v5
	v_lshlrev_b32_e32 v8, 1, v5
	v_and_b32_e32 v4, 0xc0, v4
	v_and_or_b32 v6, v5, s8, v6
	v_and_b32_e32 v7, 4, v7
	v_and_b32_e32 v8, 24, v8
	v_sub_u32_e32 v3, v3, v4
	v_mov_b32_e32 v4, 1
	v_or3_b32 v6, v6, v7, v8
	v_lshlrev_b32_e32 v7, 5, v10
	v_ashrrev_i16_sdwa v3, v4, sext(v3) dst_sel:DWORD dst_unused:UNUSED_PAD src0_sel:DWORD src1_sel:BYTE_0
	s_movk_i32 s3, 0xb00
	v_and_b32_e32 v13, 32, v7
	v_bfe_i32 v14, v3, 0, 16
	v_mul_u32_u24_e32 v6, 0xb00, v6
	v_add_u32_e32 v3, v13, v14
	v_mul_lo_u32 v5, v5, s3
	v_add_lshl_u32 v146, v6, v3, 1
	v_add_lshl_u32 v148, v3, v5, 1
	v_bfe_i32 v3, v11, 27, 1
	v_lshrrev_b32_e32 v3, 22, v3
	v_add_u32_e32 v3, v2, v3
	v_and_b32_e32 v3, 0xfffffc00, v3
	v_sub_u32_e32 v2, v2, v3
	v_lshrrev_b32_e32 v3, 4, v2
	v_ashrrev_i32_e32 v5, 31, v11
	v_bitop3_b32 v2, v3, v2, 32 bitop3:0x6c
	v_lshrrev_b32_e32 v5, 26, v5
	v_ashrrev_i32_e32 v3, 31, v2
	v_add_u32_e32 v5, v11, v5
	s_add_u32 s25, s30, 0x2100000
	v_lshrrev_b32_e32 v3, 26, v3
	v_ashrrev_i32_e32 v16, 6, v5
	s_addc_u32 s27, s31, 0
	v_add_u32_e32 v3, v2, v3
	v_lshlrev_b32_e32 v5, 3, v16
	s_add_u32 s34, s30, 0x2692c000
	v_ashrrev_i32_e32 v15, 6, v3
	v_and_b32_e32 v5, -16, v5
	s_addc_u32 s35, s31, 0
	s_ashr_i32 s37, s26, 31
	v_add_u32_e32 v5, v15, v5
	v_and_b32_e32 v6, 3, v15
	v_and_or_b32 v6, v5, s8, v6
	s_lshr_b32 s8, s37, 29
	s_add_i32 s8, s26, s8
	s_ashr_i32 s9, s8, 3
	s_and_b32 s8, s8, -8
	s_sub_i32 s8, s26, s8
	s_lshr_b32 s10, s8, 31
	s_or_b32 s10, s10, 0x90
	s_mul_i32 s8, s10, s8
	s_add_i32 s8, s8, s9
	s_mul_hi_i32 s9, s8, 0x38e38e39
	s_lshr_b32 s10, s9, 31
	s_ashr_i32 s9, s9, 3
	s_add_i32 s59, s9, s10
	s_mul_i32 s9, s59, 0xffffffdc
	s_add_i32 s8, s9, s8
	s_ashr_i32 s9, s8, 31
	s_lshr_b32 s9, s9, 27
	s_add_i32 s9, s8, s9
	s_ashr_i32 s10, s9, 5
	s_lshl_b32 s10, s10, 3
	s_sub_i32 s11, 9, s10
	s_min_i32 s11, s11, 8
	v_lshrrev_b32_e32 v7, 2, v5
	v_lshlrev_b32_e32 v8, 1, v5
	v_and_b32_e32 v3, 0xc0, v3
	s_abs_i32 s12, s11
	v_and_b32_e32 v7, 4, v7
	v_and_b32_e32 v8, 24, v8
	v_sub_u32_e32 v2, v2, v3
	v_cvt_f32_u32_e32 v3, s12
	v_or3_b32 v6, v6, v7, v8
	v_lshlrev_b32_e32 v7, 5, v16
	v_ashrrev_i16_sdwa v2, v4, sext(v2) dst_sel:DWORD dst_unused:UNUSED_PAD src0_sel:DWORD src1_sel:BYTE_0
	v_and_b32_e32 v17, 32, v7
	v_bfe_i32 v18, v2, 0, 16
	v_mul_u32_u24_e32 v6, 0xb00, v6
	v_add_u32_e32 v2, v17, v18
	v_mul_lo_u32 v4, v5, s3
	v_add_lshl_u32 v150, v6, v2, 1
	v_add_lshl_u32 v152, v2, v4, 1
	v_rcp_iflag_f32_e32 v2, v3
	s_sub_i32 s14, 0, s12
	s_andn2_b32 s9, s9, 31
	s_sub_i32 s8, s8, s9
	v_mul_f32_e32 v2, 0x4f7ffffe, v2
	v_cvt_u32_f32_e32 v2, v2
	s_abs_i32 s13, s8
	s_ashr_i32 s4, s2, 6
	s_xor_b32 s9, s8, s11
	v_readfirstlane_b32 s15, v2
	s_mul_i32 s14, s14, s15
	s_mul_hi_u32 s14, s15, s14
	s_add_i32 s15, s15, s14
	s_mul_hi_u32 s14, s13, s15
	s_mul_i32 s15, s14, s12
	s_sub_i32 s13, s13, s15
	s_ashr_i32 s5, s2, 8
	s_lshl_b32 s36, s4, 10
	s_ashr_i32 s9, s9, 31
	s_add_i32 s15, s14, 1
	s_sub_i32 s16, s13, s12
	s_cmp_ge_u32 s13, s12
	s_cselect_b32 s14, s15, s14
	s_cselect_b32 s13, s16, s13
	s_add_i32 s15, s14, 1
	s_cmp_ge_u32 s13, s12
	s_cselect_b32 s12, s15, s14
	s_xor_b32 s12, s12, s9
	s_sub_i32 s61, s12, s9
	s_mul_i32 s9, s61, s11
	s_sub_i32 s8, s8, s9
	s_add_i32 s60, s8, s10
	s_mul_i32 s9, s61, 0x160000
	s_mul_hi_i32 s8, s61, 0x160000
	s_add_u32 s18, s25, s9
	s_addc_u32 s19, s27, s8
	s_add_i32 s38, s36, 0
	s_add_i32 m0, s38, 0x10000
	s_mul_i32 s9, s59, 0xc60000
	global_load_lds_dwordx4 v150, s[18:19]
	s_add_i32 m0, s38, 0x12000
	s_mul_hi_i32 s8, s59, 0xc60000
	s_add_u32 s12, s34, s9
	s_addc_u32 s13, s35, s8
	s_add_u32 s8, s18, 0xb0000
	global_load_lds_dwordx4 v146, s[18:19]
	s_addc_u32 s9, s19, 0
	s_add_i32 m0, s38, 0x14000
	s_mul_i32 s11, s60, 0x160000
	global_load_lds_dwordx4 v150, s[8:9]
	s_add_i32 m0, s38, 0x16000
	s_mul_hi_i32 s10, s60, 0x160000
	s_add_u32 s16, s12, s11
	s_addc_u32 s17, s13, s10
	s_add_i32 s39, s38, 0x2000
	global_load_lds_dwordx4 v146, s[8:9]
	s_mov_b32 m0, s38
	s_add_u32 s8, s16, 0xb0000
	global_load_lds_dwordx4 v152, s[16:17]
	s_mov_b32 m0, s39
	s_addc_u32 s9, s17, 0
	s_add_i32 s40, s38, 0x4000
	global_load_lds_dwordx4 v148, s[16:17]
	s_mov_b32 m0, s40
	s_add_i32 s41, s38, 0x6000
	global_load_lds_dwordx4 v152, s[8:9]
	s_mov_b32 m0, s41
	v_mov_b32_e32 v151, 0
	global_load_lds_dwordx4 v148, s[8:9]
	v_mov_b32_e32 v147, v151
	v_mov_b32_e32 v153, v151
	v_mov_b32_e32 v149, v151
	s_cmp_eq_u32 s5, 1
	s_mov_b32 s42, 0
	v_lshl_add_u64 v[8:9], s[18:19], 0, v[150:151]
	v_lshl_add_u64 v[6:7], s[18:19], 0, v[146:147]
	v_lshl_add_u64 v[2:3], s[16:17], 0, v[152:153]
	s_cselect_b64 s[8:9], -1, 0
	s_cmp_lg_u32 s5, 1
	v_lshl_add_u64 v[4:5], s[16:17], 0, v[148:149]
	s_cbranch_scc1 .LBB0_1133
	s_barrier
